# hg_h1 item prologue: both value-tile loads and the four forget-gate loads issued together before the barrier (one round trip instead of three); plus hg_h3 load batching
# speedup vs baseline: 1.0098x; 1.0014x over previous
.LBB0_955:
	s_and_b32 s6, s13, 0xffffffc0
	s_and_b32 s7, s12, 0x180
	v_add_u32_e32 v2, s6, v54
	v_mov_b64_e32 v[6:7], s[4:5]
	v_readlane_b32 s8, v252, 27
	v_mad_i64_i32 v[2:3], s[0:1], v2, s37, v[6:7]
	v_readlane_b32 s9, v252, 28
	s_lshl_b32 s8, s7, 1
	s_movk_i32 s3, 0x2000
	v_lshl_add_u64 v[2:3], v[2:3], 0, s[8:9]
	v_lshl_add_u64 v[2:3], v[2:3], 0, v[0:1]
	v_add_co_u32_e32 v2, vcc, s3, v2
	s_nop 1
	v_addc_co_u32_e32 v3, vcc, 0, v3, vcc
	global_load_dwordx4 v[22:25], v[2:3], off
	v_mov_b32_e32 v51, v1
	v_add_u32_e32 v2, s6, v55
	v_mad_i64_i32 v[2:3], s[0:1], v2, s37, v[6:7]
	v_lshl_add_u64 v[2:3], v[2:3], 0, s[8:9]
	v_lshl_add_u64 v[2:3], v[2:3], 0, v[0:1]
	v_add_co_u32_e32 v2, vcc, s3, v2
	s_nop 1
	v_addc_co_u32_e32 v3, vcc, 0, v3, vcc
	global_load_dwordx4 v[26:29], v[2:3], off
	v_or_b32_e32 v2, s6, v52
	v_mad_i64_i32 v[2:3], s[0:1], v2, s37, v[6:7]
	v_readlane_b32 s0, v254, 46
	v_readlane_b32 s1, v254, 47
	s_mov_b32 s1, s9
	s_mov_b32 s6, s0
	v_lshl_add_u64 v[2:3], v[2:3], 0, s[0:1]
	v_writelane_b32 v252, s0, 27
	v_lshl_add_u64 v[2:3], v[2:3], 0, s[8:9]
	v_lshl_add_u64 v[2:3], v[2:3], 0, v[50:51]
	v_writelane_b32 v252, s1, 28
	s_mov_b64 s[0:1], 0x1800
	v_lshl_add_u64 v[10:11], v[2:3], 0, s[0:1]
	v_add_co_u32_e32 v2, vcc, 0x1000, v2
	v_readlane_b32 s0, v252, 35
	s_nop 0
	v_addc_co_u32_e32 v3, vcc, 0, v3, vcc
	global_load_dwordx4 v[14:17], v[2:3], off offset:2048
	s_nop 0
	global_load_dwordx4 v[2:5], v[10:11], off offset:48
	global_load_dwordx4 v[6:9], v[10:11], off offset:32
	s_nop 0
	global_load_dwordx4 v[10:13], v[10:11], off offset:16
	v_writelane_b32 v254, s6, 46
	v_readlane_b32 s1, v252, 36
	s_and_b64 vcc, exec, s[0:1]
	v_writelane_b32 v254, s7, 47
	s_mov_b64 s[6:7], -1
	s_barrier
	s_waitcnt vmcnt(5)
	ds_write_b16 v56, v22 offset:36864
	ds_write_b16_d16_hi v56, v22 offset:37008
	ds_write_b16 v56, v23 offset:37152
	ds_write_b16_d16_hi v56, v23 offset:37296
	ds_write_b16 v56, v24 offset:37440
	ds_write_b16_d16_hi v56, v24 offset:37584
	ds_write_b16 v56, v25 offset:37728
	ds_write_b16_d16_hi v56, v25 offset:37872
	s_waitcnt vmcnt(4)
	ds_write_b16 v57, v26 offset:36864
	ds_write_b16_d16_hi v57, v26 offset:37008
	ds_write_b16 v57, v27 offset:37152
	ds_write_b16_d16_hi v57, v27 offset:37296
	ds_write_b16 v57, v28 offset:37440
	ds_write_b16_d16_hi v57, v28 offset:37584
	ds_write_b16 v57, v29 offset:37728
	ds_write_b16_d16_hi v57, v29 offset:37872
	s_waitcnt vmcnt(3)
	v_lshlrev_b32_e32 v28, 16, v14
	s_cbranch_vccz .LBB0_957
	s_nop 0
	v_add_f32_dpp v18, v28, v28 row_shl:1 row_mask:0xf bank_mask:0xf bound_ctrl:1
	s_mov_b64 s[6:7], 0
	s_nop 0
	v_add_f32_dpp v18, v18, v18 row_shl:2 row_mask:0xf bank_mask:0xf bound_ctrl:1
	s_nop 1
	v_add_f32_dpp v19, v18, v18 row_shl:4 row_mask:0xf bank_mask:0xf bound_ctrl:1
	s_nop 1
	v_mov_b32_dpp v20, v19 row_shl:8 row_mask:0xf bank_mask:0xf bound_ctrl:1
